# barrier poll cadence tightened: s_sleep 1 between generation-word polls (was 3)
# baseline (speedup 1.0000x reference)
; __device__ __forceinline__ unsigned xb_ld(unsigned* p)              { return __hip_atomic_load(p, __ATOMIC_RELAXED, __HIP_MEMORY_SCOPE_AGENT); }
; __device__ __forceinline__ unsigned xb_add(unsigned* p, unsigned v) { return __hip_atomic_fetch_add(p, v, __ATOMIC_RELAXED, __HIP_MEMORY_SCOPE_AGENT); }
; #define XB_SPIN(cond, bar) do { unsigned _sp = 0; while (cond) { __builtin_amdgcn_s_sleep(1); \
;     if ((++_sp & 255u) == 0u) { if (xb_ld(&(bar)[XB_TMO])) break; if (_sp > XB_SPIN_CAP) { atomicAdd(&(bar)[XB_TMO], 1u); break; } } } } while (0)
; __device__ __forceinline__ void xcd_barrier(const XcdBarrier& b) {
;     ...
;         const unsigned old = xb_add(&bar[XB_XSUB(b.x)], 1u);
;         const unsigned gen = old / nloc;
;         if (old + 1u == (gen + 1u) * nloc) {
;             __builtin_amdgcn_fence(__ATOMIC_RELEASE, "agent");
;             asm volatile("s_waitcnt vmcnt(0)" ::: "memory");
;             const unsigned og = xb_add(&bar[XB_TOP], 1u);
;             const unsigned tg = og / nx;
;             if (og + 1u == (tg + 1u) * nx) xb_add(&bar[XB_TOPGEN], 1u);
;             else XB_SPIN(xb_ld(&bar[XB_TOPGEN]) == tg, bar);
;             __builtin_amdgcn_fence(__ATOMIC_ACQUIRE, "agent");
;             xb_add(&bar[XB_XGEN(b.x)], 1u);
;             asm volatile("s_waitcnt vmcnt(0)" ::: "memory");
;         } else {
;             XB_SPIN(xb_ld(&bar[XB_XGEN(b.x)]) == gen, bar);
.LBB0_129:
	v_readlane_b32 s4, v236, 18
	s_lshl_b32 s4, s4, 8
	s_add_u32 s4, s28, s4
	s_addc_u32 s5, s29, 0
	v_mov_b32_e32 v1, 0x1000
	v_mov_b32_e32 v3, 1
	global_atomic_add v3, v1, v3, s[4:5] offset:1024 sc0
	v_cvt_f32_u32_e32 v1, v2
	v_sub_u32_e32 v4, 0, v2
	v_rcp_iflag_f32_e32 v1, v1
	s_nop 0
	v_mul_f32_e32 v1, 0x4f7ffffe, v1
	v_cvt_u32_f32_e32 v1, v1
	v_mul_lo_u32 v4, v4, v1
	v_mul_hi_u32 v4, v1, v4
	v_add_u32_e32 v1, v1, v4
	s_waitcnt vmcnt(0)
	v_mul_hi_u32 v1, v3, v1
	v_mul_lo_u32 v4, v1, v2
	v_sub_u32_e32 v4, v3, v4
	v_add_u32_e32 v5, 1, v1
	v_cmp_ge_u32_e32 vcc, v4, v2
	v_add_u32_e32 v3, 1, v3
	s_nop 0
	v_cndmask_b32_e32 v1, v1, v5, vcc
	v_sub_u32_e32 v5, v4, v2
	v_cndmask_b32_e32 v4, v4, v5, vcc
	v_add_u32_e32 v5, 1, v1
	v_cmp_ge_u32_e32 vcc, v4, v2
	s_nop 1
	v_cndmask_b32_e32 v1, v1, v5, vcc
	v_mul_lo_u32 v4, v2, v1
	v_add_u32_e32 v2, v4, v2
	v_cmp_ne_u32_e32 vcc, v3, v2
	s_and_saveexec_b64 s[6:7], vcc
	s_xor_b64 s[6:7], exec, s[6:7]
	s_cbranch_execz .LBB0_143
	s_waitcnt lgkmcnt(0)
	v_mov_b32_e32 v0, 0x3000
	global_load_dword v0, v0, s[28:29] offset:1280 sc1
	s_add_u32 s10, s28, 0x3500
	s_addc_u32 s11, s29, 0
	s_waitcnt vmcnt(0)
	v_cmp_eq_u32_e32 vcc, v0, v1
	s_and_saveexec_b64 s[8:9], vcc
	s_cbranch_execz .LBB0_142
	v_mov_b32_e32 v0, 0
	s_mov_b64 s[12:13], exec
	s_mov_b64 s[14:15], -1
	s_mov_b32 s22, 0
	global_load_dword v2, v0, s[10:11] sc1
	s_sleep 1
	global_load_dword v3, v0, s[10:11] sc1
	s_sleep 1
	global_load_dword v4, v0, s[10:11] sc1
	s_sleep 1
	global_load_dword v5, v0, s[10:11] sc1
.Lpoll_loop_0:
	s_waitcnt vmcnt(3)
	v_cmp_ne_u32_e32 vcc, v2, v1
	s_cbranch_vccnz .Lpoll_done_0
	global_load_dword v2, v0, s[10:11] sc1
	s_sleep 1
	s_waitcnt vmcnt(3)
	v_cmp_ne_u32_e32 vcc, v3, v1
	s_cbranch_vccnz .Lpoll_done_0
	global_load_dword v3, v0, s[10:11] sc1
	s_sleep 1
	s_waitcnt vmcnt(3)
	v_cmp_ne_u32_e32 vcc, v4, v1
	s_cbranch_vccnz .Lpoll_done_0
	global_load_dword v4, v0, s[10:11] sc1
	s_sleep 1
	s_waitcnt vmcnt(3)
	v_cmp_ne_u32_e32 vcc, v5, v1
	s_cbranch_vccnz .Lpoll_done_0
	global_load_dword v5, v0, s[10:11] sc1
	s_sleep 1
	s_add_i32 s22, s22, 1
	s_cmp_lt_u32 s22, 0x100000
	s_cbranch_scc1 .Lpoll_loop_0
	s_mov_b64 s[14:15], 0
